# one s_nop pad so code after the MLA prio block keeps the baseline 8-byte phase
# speedup vs baseline: 1.0031x; 1.0031x over previous
; #define DMA_K(t, slot) do { const bf16_t* s_ = Knp + (long)(t) * (KVBLK * LDK); const unsigned d_ = (unsigned)__builtin_amdgcn_readfirstlane(kn_dst + (slot) * SHM_KN); \
;     glds16s(s_, kn_off, d_); glds16s(s_ + 16 * LDK, kn_off, d_ + 4096); glds16s(Krp + (long)(t) * (KVBLK * 64), kr_off, (unsigned)__builtin_amdgcn_readfirstlane(kr_dst + (slot) * SHM_KR)); } while (0)
; #define DMA_V(t, slot) do { const bf16_t* s_ = Vp + (long)(t) * (KVBLK * LDK); const unsigned d_ = (unsigned)__builtin_amdgcn_readfirstlane(v_dst + (slot) * SHM_V); \
;     glds16s(s_, v_off, d_); glds16s(s_ + 32 * LDK, v_off, d_ + 8192); } while (0)
; __device__ __forceinline__ void mla_unit(char* lds, const bf16_t* __restrict__ Qp, const bf16_t* __restrict__ Knp, const bf16_t* __restrict__ Vp, ...
;     ...
;   const int pk = (wid & 3) + 8 * (wid >> 2);
;   const int krow_n = 4 * pk + (lane >> 4);
;   const unsigned kn_off = (unsigned)(krow_n * LDK + (((lane & 15) ^ (krow_n & 15)) << 3)) * 2u;
;   const int krow_r = 8 * wid + (lane >> 3);
;   const unsigned kr_off = (unsigned)(krow_r * 64 + (((lane & 7) ^ ((krow_r >> 1) & 7)) << 3)) * 2u;
;   const int vst_ = 2 * wid + (lane >> 5), vkk = (vst_ >> 2) * 8 + ((lane >> 2) & 7), vkey = (vkk & ~0xC) | ((vkk & 4) << 1) | ((vkk & 8) >> 1), vcol = (vst_ & 3) * 32 + (lane & 3) * 8;
;   const unsigned v_off = (unsigned)(vkey * LDK + vcol) * 2u;
;   const unsigned kn_dst = lds0 + P_KN + pk * 1024, kr_dst = lds0 + P_KR + wid * 1024, v_dst = lds0 + P_V + wid * 1024;
;     ...
;   if (first) { DMA_K(0, 0); DMA_V(0, 0); DMA_K(1, 1); DMA_V(1, 1); DMA_K(2, 2); }
.Lmla_prio_skip:
	s_nop 0
	s_ashr_i32 s5, s0, 5
	s_and_b32 s1, s8, 3
	s_and_b32 s5, s5, -8
	s_or_b32 s1, s1, s5
	s_lshl_b32 s5, s1, 2
	s_ashr_i32 s12, s0, 4
	v_bfe_u32 v1, v50, 4, 2
	s_ashr_i32 s7, s6, 31
	s_and_b32 s13, s12, 0x7ffff0
	s_lshr_b32 s12, s12, 1
	v_or_b32_e32 v2, s5, v1
	v_bitop3_b32 v1, s5, v50, v1 bitop3:0x36
	s_bfe_u32 s38, s74, 0x40005
	s_lshl_b64 s[30:31], s[6:7], 22
	s_lshl_b64 s[36:37], s[6:7], 20
	s_lshl_b32 s9, s8, 1
	s_and_b32 s12, s12, 4
	s_lshl_b32 s72, s1, 10
	v_lshlrev_b32_e32 v2, 9, v2
	v_lshlrev_b32_e32 v1, 4, v1
	s_cmp_lg_u32 0, -1
	v_and_or_b32 v197, v1, s53, v2
	v_bfe_u32 v1, v50, 3, 3
	s_cselect_b32 s1, 0, 0
	s_lshl_b32 s71, s8, 10
	v_lshl_or_b32 v1, s8, 3, v1
	s_add_i32 s14, s1, s72
	s_add_i32 s73, s71, s1
	v_lshlrev_b32_e32 v2, 7, v1
	v_lshrrev_b32_e32 v1, 1, v1
	s_add_i32 s76, s14, 0xc000
	s_add_i32 s75, s73, 0x18000
	v_readlane_b32 s1, v253, 3
	v_xor_b32_e32 v1, v1, v50
	s_cmp_lg_u32 s74, s1
	v_lshlrev_b32_e32 v1, 4, v1
	s_movk_i32 s1, 0x70
	v_and_or_b32 v198, v1, s1, v2
	v_lshrrev_b32_e32 v1, 2, v50
	v_lshrrev_b32_e32 v2, 1, v50
	v_bfe_u32 v49, v50, 5, 1
	v_and_or_b32 v1, v1, 3, s13
	v_and_b32_e32 v2, 8, v2
	v_lshlrev_b32_e32 v48, 4, v50
	v_or3_b32 v1, v1, v2, s12
	v_and_or_b32 v2, s9, 2, v49
	v_and_b32_e32 v3, 48, v48
	v_lshl_or_b32 v2, v2, 6, v3
	v_lshl_or_b32 v199, v1, 9, v2
	s_cbranch_scc1 .LBB0_238
	s_lshl_b32 s1, s38, 23
	v_readlane_b32 s5, v254, 62
	s_add_u32 s1, s5, s1
	v_readlane_b32 s5, v254, 63
	s_addc_u32 s5, s5, 0
	s_add_u32 s12, s1, s30
	s_addc_u32 s13, s5, s31
	s_add_u32 s14, s12, 0x100
	s_addc_u32 s15, s13, 0
	s_add_u32 s16, s26, s36
	s_addc_u32 s17, s27, s37
	s_mov_b32 s1, m0
	s_mov_b32 m0, s76
	s_nop 0
	global_load_lds_dwordx4 v197, s[12:13]
	s_mov_b32 m0, s1
	s_add_u32 s18, s12, 0x2000
	s_addc_u32 s19, s13, 0
	s_add_i32 s1, s76, 0x1000
	s_mov_b32 s5, m0
	s_mov_b32 m0, s1
	s_nop 0
	global_load_lds_dwordx4 v197, s[18:19]
	s_mov_b32 m0, s5
	s_mov_b32 s1, m0
	s_mov_b32 m0, s75
	s_nop 0
	global_load_lds_dwordx4 v198, s[16:17]
	s_mov_b32 m0, s1
	s_nop 0
	s_mov_b32 s1, m0
	s_mov_b32 m0, s73
	s_nop 0
	global_load_lds_dwordx4 v199, s[14:15]
	s_mov_b32 m0, s1
	s_add_u32 s14, s12, 0x4100
	s_addc_u32 s15, s13, 0
	s_add_i32 s1, s73, 0x2000
	s_mov_b32 s5, m0
	s_mov_b32 m0, s1
	s_nop 0
	global_load_lds_dwordx4 v199, s[14:15]
	s_mov_b32 m0, s5
	s_add_u32 s14, s12, 0x8000
	s_addc_u32 s15, s13, 0
	s_cmp_lg_u32 0, -1
	s_cselect_b32 s1, 0, 0
	s_add_i32 s5, s1, s72
	s_add_i32 s9, s5, 0x10000
	s_mov_b32 s18, m0
	s_mov_b32 m0, s9
	s_nop 0
	global_load_lds_dwordx4 v197, s[14:15]
	s_mov_b32 m0, s18
	s_add_u32 s14, s12, 0xa000
	s_addc_u32 s15, s13, 0
	s_add_i32 s9, s5, 0x11000
	s_mov_b32 s18, m0
	s_mov_b32 m0, s9
	s_nop 0
	global_load_lds_dwordx4 v197, s[14:15]
	s_mov_b32 m0, s18
	s_add_u32 s14, s16, 0x2000
	s_addc_u32 s15, s17, 0
	s_add_i32 s1, s1, s71
	s_add_i32 s9, s1, 0x1a000
	s_mov_b32 s18, m0
	s_mov_b32 m0, s9
	s_nop 0
	global_load_lds_dwordx4 v198, s[14:15]
	s_mov_b32 m0, s18
	s_add_u32 s14, s12, 0x8100
	s_addc_u32 s15, s13, 0
	s_add_i32 s9, s1, 0x4000
	s_mov_b32 s18, m0
	s_mov_b32 m0, s9
	s_nop 0
	global_load_lds_dwordx4 v199, s[14:15]
	s_mov_b32 m0, s18
	s_add_u32 s14, s12, 0xc100
	s_addc_u32 s15, s13, 0
	s_add_i32 s9, s1, 0x6000
	s_mov_b32 s18, m0
	s_mov_b32 m0, s9
	s_nop 0
	global_load_lds_dwordx4 v199, s[14:15]
	s_mov_b32 m0, s18
	s_add_u32 s14, s12, 0x10000
	s_addc_u32 s15, s13, 0
	s_add_i32 s9, s5, 0x14000
	s_add_u32 s12, s12, 0x12000
	s_mov_b32 s18, m0
	s_mov_b32 m0, s9
	s_nop 0
	global_load_lds_dwordx4 v197, s[14:15]
	s_mov_b32 m0, s18
	s_addc_u32 s13, s13, 0
	s_add_i32 s5, s5, 0x15000
	s_mov_b32 s9, m0
	s_mov_b32 m0, s5
	s_nop 0
	global_load_lds_dwordx4 v197, s[12:13]
	s_mov_b32 m0, s9
	s_add_u32 s12, s16, 0x4000
	s_addc_u32 s13, s17, 0
	s_add_i32 s1, s1, 0x1c000
	s_mov_b32 s5, m0
	s_mov_b32 m0, s1
	s_nop 0
	global_load_lds_dwordx4 v198, s[12:13]
	s_mov_b32 m0, s5
